# s5y items: mirrored position quarter for waves 4-7 (one long + one short wave per SIMD) and intra-chunk loop rewritten with a 16-slot sliding fragment ring (2 LDS reads per k-step, no per-MFMA guards)
# baseline (speedup 1.0000x reference)
; #define LAS __attribute__((address_space(3)))
; __device__ __forceinline__ void s5y_item(ArgsRef A, int item, LAS unsigned char* lds, int tid, int lane, int wave) {
;     ...
;     f32x4 acc[16];
; #pragma unroll
;     for (int i = 0; i < 16; ++i) acc[i] = (f32x4){0.f, 0.f, 0.f, 0.f};
;     for (int kb = 0; kb < nks; kb += 8) {
;         if (kb + 8 < nks) {
; #pragma unroll
;             for (int i = 0; i < 8; ++i) nxt[i] = *(const bf16x8*)(ubq + (size_t)(2 * (kb + 8 + i)) * NIN); }
; #pragma unroll
;         for (int i = 0; i < 8; ++i) { bf16x8 af[16];
; #pragma unroll
;             for (int tt = 0; tt < 16; ++tt) { const int j = 16 * tq + tt - 2 * (kb + i); af[tt] = *(const LAS bf16x8*)(lds + (j >= 0 ? j : 0) * 1024 + lane * 16); }
;             __builtin_amdgcn_sched_barrier(0);
; #pragma unroll
;             for (int tt = 0; tt < 16; ++tt) { const int j = 16 * tq + tt - 2 * (kb + i); if (j >= 0) acc[tt] = __builtin_amdgcn_mfma_f32_16x16x32_bf16(af[tt], cur[i], acc[tt], 0, 0, 0); }
;             __builtin_amdgcn_sched_barrier(0); }
; #pragma unroll
;         for (int i = 0; i < 8; ++i) cur[i] = nxt[i];
;     }
.LBB0_578:
	s_waitcnt vmcnt(0)
	v_mov_b64_e32 v[34:35], 0
	v_mov_b64_e32 v[36:37], 0
	v_mov_b64_e32 v[38:39], 0
	v_mov_b64_e32 v[40:41], 0
	v_mov_b64_e32 v[42:43], 0
	v_mov_b64_e32 v[44:45], 0
	v_mov_b64_e32 v[46:47], 0
	v_mov_b64_e32 v[48:49], 0
	v_mov_b64_e32 v[50:51], 0
	v_mov_b64_e32 v[52:53], 0
	v_mov_b64_e32 v[54:55], 0
	v_mov_b64_e32 v[56:57], 0
	v_mov_b64_e32 v[58:59], 0
	v_mov_b64_e32 v[60:61], 0
	v_mov_b64_e32 v[62:63], 0
	v_mov_b64_e32 v[64:65], 0
	v_mov_b64_e32 v[66:67], 0
	v_mov_b64_e32 v[68:69], 0
	v_mov_b64_e32 v[70:71], 0
	v_mov_b64_e32 v[72:73], 0
	v_mov_b64_e32 v[74:75], 0
	v_mov_b64_e32 v[76:77], 0
	v_mov_b64_e32 v[78:79], 0
	v_mov_b64_e32 v[80:81], 0
	v_mov_b64_e32 v[82:83], 0
	v_mov_b64_e32 v[84:85], 0
	v_mov_b64_e32 v[86:87], 0
	v_mov_b64_e32 v[88:89], 0
	v_mov_b64_e32 v[90:91], 0
	v_mov_b64_e32 v[92:93], 0
	v_mov_b64_e32 v[94:95], 0
	v_mov_b64_e32 v[96:97], 0
	s_lshl_b32 s48, s54, 4
	v_lshl_add_u32 v199, v220, 4, 0
	s_lshl_b32 s42, s36, 10
	v_add_u32_e32 v0, s42, v199
	ds_read_b128 v[134:137], v0
	ds_read_b128 v[138:141], v0 offset:1024
	ds_read_b128 v[142:145], v0 offset:2048
	ds_read_b128 v[146:149], v0 offset:3072
	ds_read_b128 v[150:153], v0 offset:4096
	ds_read_b128 v[154:157], v0 offset:5120
	ds_read_b128 v[158:161], v0 offset:6144
	ds_read_b128 v[162:165], v0 offset:7168
	ds_read_b128 v[166:169], v0 offset:8192
	ds_read_b128 v[170:173], v0 offset:9216
	ds_read_b128 v[174:177], v0 offset:10240
	ds_read_b128 v[178:181], v0 offset:11264
	ds_read_b128 v[182:185], v0 offset:12288
	ds_read_b128 v[186:189], v0 offset:13312
	ds_read_b128 v[190:193], v0 offset:14336
	ds_read_b128 v[194:197], v0 offset:15360
	v_add_u32_e32 v2, 0xffffc000, v0
	s_mov_b32 s40, 0xa000
	s_mov_b32 s41, 0
	s_lshr_b32 s42, s36, 4
	s_waitcnt lgkmcnt(0)
	s_cmp_eq_u32 s42, 0
	s_cbranch_scc1 .Ls5y_tail
.Ls5y_full:
	s_waitcnt vmcnt(7)
	v_mfma_f32_16x16x32_bf16 v[34:37], v[194:197], v[98:101], v[34:37]
	v_mfma_f32_16x16x32_bf16 v[38:41], v[190:193], v[98:101], v[38:41]
	ds_read_b128 v[190:193], v2 offset:14336
	ds_read_b128 v[194:197], v2 offset:15360
	v_mfma_f32_16x16x32_bf16 v[42:45], v[186:189], v[98:101], v[42:45]
	v_mfma_f32_16x16x32_bf16 v[46:49], v[182:185], v[98:101], v[46:49]
	v_mfma_f32_16x16x32_bf16 v[50:53], v[178:181], v[98:101], v[50:53]
	v_mfma_f32_16x16x32_bf16 v[54:57], v[174:177], v[98:101], v[54:57]
	v_mfma_f32_16x16x32_bf16 v[58:61], v[170:173], v[98:101], v[58:61]
	v_mfma_f32_16x16x32_bf16 v[62:65], v[166:169], v[98:101], v[62:65]
	v_mfma_f32_16x16x32_bf16 v[66:69], v[162:165], v[98:101], v[66:69]
	v_mfma_f32_16x16x32_bf16 v[70:73], v[158:161], v[98:101], v[70:73]
	v_mfma_f32_16x16x32_bf16 v[74:77], v[154:157], v[98:101], v[74:77]
	v_mfma_f32_16x16x32_bf16 v[78:81], v[150:153], v[98:101], v[78:81]
	v_mfma_f32_16x16x32_bf16 v[82:85], v[146:149], v[98:101], v[82:85]
	v_mfma_f32_16x16x32_bf16 v[86:89], v[142:145], v[98:101], v[86:89]
	s_waitcnt lgkmcnt(2)
	v_mfma_f32_16x16x32_bf16 v[90:93], v[138:141], v[98:101], v[90:93]
	v_mfma_f32_16x16x32_bf16 v[94:97], v[134:137], v[98:101], v[94:97]
	v_lshl_add_u64 v[102:103], s[40:41], 0, v[200:201]
	s_add_u32 s40, s40, 0x1400
	s_addc_u32 s41, s41, 0
	global_load_dwordx4 v[98:101], v[102:103], off offset:1280
	s_waitcnt vmcnt(7)
	v_mfma_f32_16x16x32_bf16 v[34:37], v[186:189], v[30:33], v[34:37]
	v_mfma_f32_16x16x32_bf16 v[38:41], v[182:185], v[30:33], v[38:41]
	ds_read_b128 v[182:185], v2 offset:12288
	ds_read_b128 v[186:189], v2 offset:13312
	v_mfma_f32_16x16x32_bf16 v[42:45], v[178:181], v[30:33], v[42:45]
	v_mfma_f32_16x16x32_bf16 v[46:49], v[174:177], v[30:33], v[46:49]
	v_mfma_f32_16x16x32_bf16 v[50:53], v[170:173], v[30:33], v[50:53]
	v_mfma_f32_16x16x32_bf16 v[54:57], v[166:169], v[30:33], v[54:57]
	v_mfma_f32_16x16x32_bf16 v[58:61], v[162:165], v[30:33], v[58:61]
	v_mfma_f32_16x16x32_bf16 v[62:65], v[158:161], v[30:33], v[62:65]
	v_mfma_f32_16x16x32_bf16 v[66:69], v[154:157], v[30:33], v[66:69]
	v_mfma_f32_16x16x32_bf16 v[70:73], v[150:153], v[30:33], v[70:73]
	v_mfma_f32_16x16x32_bf16 v[74:77], v[146:149], v[30:33], v[74:77]
	v_mfma_f32_16x16x32_bf16 v[78:81], v[142:145], v[30:33], v[78:81]
	v_mfma_f32_16x16x32_bf16 v[82:85], v[138:141], v[30:33], v[82:85]
	v_mfma_f32_16x16x32_bf16 v[86:89], v[134:137], v[30:33], v[86:89]
	s_waitcnt lgkmcnt(2)
	v_mfma_f32_16x16x32_bf16 v[90:93], v[194:197], v[30:33], v[90:93]
	v_mfma_f32_16x16x32_bf16 v[94:97], v[190:193], v[30:33], v[94:97]
	v_lshl_add_u64 v[102:103], s[40:41], 0, v[200:201]
	s_add_u32 s40, s40, 0x1400
	s_addc_u32 s41, s41, 0
	global_load_dwordx4 v[30:33], v[102:103], off offset:1280
	s_waitcnt vmcnt(7)
	v_mfma_f32_16x16x32_bf16 v[34:37], v[178:181], v[26:29], v[34:37]
	v_mfma_f32_16x16x32_bf16 v[38:41], v[174:177], v[26:29], v[38:41]
	ds_read_b128 v[174:177], v2 offset:10240
	ds_read_b128 v[178:181], v2 offset:11264
	v_mfma_f32_16x16x32_bf16 v[42:45], v[170:173], v[26:29], v[42:45]
	v_mfma_f32_16x16x32_bf16 v[46:49], v[166:169], v[26:29], v[46:49]
	v_mfma_f32_16x16x32_bf16 v[50:53], v[162:165], v[26:29], v[50:53]
	v_mfma_f32_16x16x32_bf16 v[54:57], v[158:161], v[26:29], v[54:57]
	v_mfma_f32_16x16x32_bf16 v[58:61], v[154:157], v[26:29], v[58:61]
	v_mfma_f32_16x16x32_bf16 v[62:65], v[150:153], v[26:29], v[62:65]
	v_mfma_f32_16x16x32_bf16 v[66:69], v[146:149], v[26:29], v[66:69]
	v_mfma_f32_16x16x32_bf16 v[70:73], v[142:145], v[26:29], v[70:73]
	v_mfma_f32_16x16x32_bf16 v[74:77], v[138:141], v[26:29], v[74:77]
	v_mfma_f32_16x16x32_bf16 v[78:81], v[134:137], v[26:29], v[78:81]
	v_mfma_f32_16x16x32_bf16 v[82:85], v[194:197], v[26:29], v[82:85]
	v_mfma_f32_16x16x32_bf16 v[86:89], v[190:193], v[26:29], v[86:89]
	s_waitcnt lgkmcnt(2)
; #define LAS __attribute__((address_space(3)))
; __device__ __forceinline__ void s5y_item(ArgsRef A, int item, LAS unsigned char* lds, int tid, int lane, int wave) {
;     ...
;     f32x4 acc[16];
; #pragma unroll
;     for (int i = 0; i < 16; ++i) acc[i] = (f32x4){0.f, 0.f, 0.f, 0.f};
;     for (int kb = 0; kb < nks; kb += 8) {
;         if (kb + 8 < nks) {
; #pragma unroll
;             for (int i = 0; i < 8; ++i) nxt[i] = *(const bf16x8*)(ubq + (size_t)(2 * (kb + 8 + i)) * NIN); }
; #pragma unroll
;         for (int i = 0; i < 8; ++i) { bf16x8 af[16];
; #pragma unroll
;             for (int tt = 0; tt < 16; ++tt) { const int j = 16 * tq + tt - 2 * (kb + i); af[tt] = *(const LAS bf16x8*)(lds + (j >= 0 ? j : 0) * 1024 + lane * 16); }
;             __builtin_amdgcn_sched_barrier(0);
; #pragma unroll
;             for (int tt = 0; tt < 16; ++tt) { const int j = 16 * tq + tt - 2 * (kb + i); if (j >= 0) acc[tt] = __builtin_amdgcn_mfma_f32_16x16x32_bf16(af[tt], cur[i], acc[tt], 0, 0, 0); }
;             __builtin_amdgcn_sched_barrier(0); }
; #pragma unroll
;         for (int i = 0; i < 8; ++i) cur[i] = nxt[i];
;     }
	v_mfma_f32_16x16x32_bf16 v[90:93], v[186:189], v[26:29], v[90:93]
	v_mfma_f32_16x16x32_bf16 v[94:97], v[182:185], v[26:29], v[94:97]
	v_lshl_add_u64 v[102:103], s[40:41], 0, v[200:201]
	s_add_u32 s40, s40, 0x1400
	s_addc_u32 s41, s41, 0
	global_load_dwordx4 v[26:29], v[102:103], off offset:1280
	s_waitcnt vmcnt(7)
	v_mfma_f32_16x16x32_bf16 v[34:37], v[170:173], v[22:25], v[34:37]
	v_mfma_f32_16x16x32_bf16 v[38:41], v[166:169], v[22:25], v[38:41]
	ds_read_b128 v[166:169], v2 offset:8192
	ds_read_b128 v[170:173], v2 offset:9216
	v_mfma_f32_16x16x32_bf16 v[42:45], v[162:165], v[22:25], v[42:45]
	v_mfma_f32_16x16x32_bf16 v[46:49], v[158:161], v[22:25], v[46:49]
	v_mfma_f32_16x16x32_bf16 v[50:53], v[154:157], v[22:25], v[50:53]
	v_mfma_f32_16x16x32_bf16 v[54:57], v[150:153], v[22:25], v[54:57]
	v_mfma_f32_16x16x32_bf16 v[58:61], v[146:149], v[22:25], v[58:61]
	v_mfma_f32_16x16x32_bf16 v[62:65], v[142:145], v[22:25], v[62:65]
	v_mfma_f32_16x16x32_bf16 v[66:69], v[138:141], v[22:25], v[66:69]
	v_mfma_f32_16x16x32_bf16 v[70:73], v[134:137], v[22:25], v[70:73]
	v_mfma_f32_16x16x32_bf16 v[74:77], v[194:197], v[22:25], v[74:77]
	v_mfma_f32_16x16x32_bf16 v[78:81], v[190:193], v[22:25], v[78:81]
	v_mfma_f32_16x16x32_bf16 v[82:85], v[186:189], v[22:25], v[82:85]
	v_mfma_f32_16x16x32_bf16 v[86:89], v[182:185], v[22:25], v[86:89]
	s_waitcnt lgkmcnt(2)
	v_mfma_f32_16x16x32_bf16 v[90:93], v[178:181], v[22:25], v[90:93]
	v_mfma_f32_16x16x32_bf16 v[94:97], v[174:177], v[22:25], v[94:97]
	v_lshl_add_u64 v[102:103], s[40:41], 0, v[200:201]
	s_add_u32 s40, s40, 0x1400
	s_addc_u32 s41, s41, 0
	global_load_dwordx4 v[22:25], v[102:103], off offset:1280
	s_waitcnt vmcnt(7)
	v_mfma_f32_16x16x32_bf16 v[34:37], v[162:165], v[18:21], v[34:37]
	v_mfma_f32_16x16x32_bf16 v[38:41], v[158:161], v[18:21], v[38:41]
	ds_read_b128 v[158:161], v2 offset:6144
	ds_read_b128 v[162:165], v2 offset:7168
	v_mfma_f32_16x16x32_bf16 v[42:45], v[154:157], v[18:21], v[42:45]
	v_mfma_f32_16x16x32_bf16 v[46:49], v[150:153], v[18:21], v[46:49]
	v_mfma_f32_16x16x32_bf16 v[50:53], v[146:149], v[18:21], v[50:53]
	v_mfma_f32_16x16x32_bf16 v[54:57], v[142:145], v[18:21], v[54:57]
	v_mfma_f32_16x16x32_bf16 v[58:61], v[138:141], v[18:21], v[58:61]
	v_mfma_f32_16x16x32_bf16 v[62:65], v[134:137], v[18:21], v[62:65]
	v_mfma_f32_16x16x32_bf16 v[66:69], v[194:197], v[18:21], v[66:69]
	v_mfma_f32_16x16x32_bf16 v[70:73], v[190:193], v[18:21], v[70:73]
	v_mfma_f32_16x16x32_bf16 v[74:77], v[186:189], v[18:21], v[74:77]
	v_mfma_f32_16x16x32_bf16 v[78:81], v[182:185], v[18:21], v[78:81]
	v_mfma_f32_16x16x32_bf16 v[82:85], v[178:181], v[18:21], v[82:85]
	v_mfma_f32_16x16x32_bf16 v[86:89], v[174:177], v[18:21], v[86:89]
	s_waitcnt lgkmcnt(2)
	v_mfma_f32_16x16x32_bf16 v[90:93], v[170:173], v[18:21], v[90:93]
	v_mfma_f32_16x16x32_bf16 v[94:97], v[166:169], v[18:21], v[94:97]
	v_lshl_add_u64 v[102:103], s[40:41], 0, v[200:201]
	s_add_u32 s40, s40, 0x1400
	s_addc_u32 s41, s41, 0
	global_load_dwordx4 v[18:21], v[102:103], off offset:1280
	s_waitcnt vmcnt(7)
	v_mfma_f32_16x16x32_bf16 v[34:37], v[154:157], v[12:15], v[34:37]
	v_mfma_f32_16x16x32_bf16 v[38:41], v[150:153], v[12:15], v[38:41]
	ds_read_b128 v[150:153], v2 offset:4096
	ds_read_b128 v[154:157], v2 offset:5120
	v_mfma_f32_16x16x32_bf16 v[42:45], v[146:149], v[12:15], v[42:45]
	v_mfma_f32_16x16x32_bf16 v[46:49], v[142:145], v[12:15], v[46:49]
	v_mfma_f32_16x16x32_bf16 v[50:53], v[138:141], v[12:15], v[50:53]
	v_mfma_f32_16x16x32_bf16 v[54:57], v[134:137], v[12:15], v[54:57]
	v_mfma_f32_16x16x32_bf16 v[58:61], v[194:197], v[12:15], v[58:61]
	v_mfma_f32_16x16x32_bf16 v[62:65], v[190:193], v[12:15], v[62:65]
	v_mfma_f32_16x16x32_bf16 v[66:69], v[186:189], v[12:15], v[66:69]
	v_mfma_f32_16x16x32_bf16 v[70:73], v[182:185], v[12:15], v[70:73]
	v_mfma_f32_16x16x32_bf16 v[74:77], v[178:181], v[12:15], v[74:77]
	v_mfma_f32_16x16x32_bf16 v[78:81], v[174:177], v[12:15], v[78:81]
	v_mfma_f32_16x16x32_bf16 v[82:85], v[170:173], v[12:15], v[82:85]
	v_mfma_f32_16x16x32_bf16 v[86:89], v[166:169], v[12:15], v[86:89]
	s_waitcnt lgkmcnt(2)
	v_mfma_f32_16x16x32_bf16 v[90:93], v[162:165], v[12:15], v[90:93]
	v_mfma_f32_16x16x32_bf16 v[94:97], v[158:161], v[12:15], v[94:97]
	v_lshl_add_u64 v[102:103], s[40:41], 0, v[200:201]
	s_add_u32 s40, s40, 0x1400
	s_addc_u32 s41, s41, 0
	global_load_dwordx4 v[12:15], v[102:103], off offset:1280
	s_waitcnt vmcnt(7)
	v_mfma_f32_16x16x32_bf16 v[34:37], v[146:149], v[8:11], v[34:37]
	v_mfma_f32_16x16x32_bf16 v[38:41], v[142:145], v[8:11], v[38:41]
	ds_read_b128 v[142:145], v2 offset:2048
	ds_read_b128 v[146:149], v2 offset:3072
	v_mfma_f32_16x16x32_bf16 v[42:45], v[138:141], v[8:11], v[42:45]
	v_mfma_f32_16x16x32_bf16 v[46:49], v[134:137], v[8:11], v[46:49]
	v_mfma_f32_16x16x32_bf16 v[50:53], v[194:197], v[8:11], v[50:53]
	v_mfma_f32_16x16x32_bf16 v[54:57], v[190:193], v[8:11], v[54:57]
	v_mfma_f32_16x16x32_bf16 v[58:61], v[186:189], v[8:11], v[58:61]
	v_mfma_f32_16x16x32_bf16 v[62:65], v[182:185], v[8:11], v[62:65]
	v_mfma_f32_16x16x32_bf16 v[66:69], v[178:181], v[8:11], v[66:69]
	v_mfma_f32_16x16x32_bf16 v[70:73], v[174:177], v[8:11], v[70:73]
	v_mfma_f32_16x16x32_bf16 v[74:77], v[170:173], v[8:11], v[74:77]
	v_mfma_f32_16x16x32_bf16 v[78:81], v[166:169], v[8:11], v[78:81]
	v_mfma_f32_16x16x32_bf16 v[82:85], v[162:165], v[8:11], v[82:85]
	v_mfma_f32_16x16x32_bf16 v[86:89], v[158:161], v[8:11], v[86:89]
	s_waitcnt lgkmcnt(2)
	v_mfma_f32_16x16x32_bf16 v[90:93], v[154:157], v[8:11], v[90:93]
	v_mfma_f32_16x16x32_bf16 v[94:97], v[150:153], v[8:11], v[94:97]
	v_lshl_add_u64 v[102:103], s[40:41], 0, v[200:201]
	s_add_u32 s40, s40, 0x1400
	s_addc_u32 s41, s41, 0
	global_load_dwordx4 v[8:11], v[102:103], off offset:1280
	s_waitcnt vmcnt(7)
; #define LAS __attribute__((address_space(3)))
; __device__ __forceinline__ void s5y_item(ArgsRef A, int item, LAS unsigned char* lds, int tid, int lane, int wave) {
;     ...
;     f32x4 acc[16];
; #pragma unroll
;     for (int i = 0; i < 16; ++i) acc[i] = (f32x4){0.f, 0.f, 0.f, 0.f};
;     for (int kb = 0; kb < nks; kb += 8) {
;         if (kb + 8 < nks) {
; #pragma unroll
;             for (int i = 0; i < 8; ++i) nxt[i] = *(const bf16x8*)(ubq + (size_t)(2 * (kb + 8 + i)) * NIN); }
; #pragma unroll
;         for (int i = 0; i < 8; ++i) { bf16x8 af[16];
; #pragma unroll
;             for (int tt = 0; tt < 16; ++tt) { const int j = 16 * tq + tt - 2 * (kb + i); af[tt] = *(const LAS bf16x8*)(lds + (j >= 0 ? j : 0) * 1024 + lane * 16); }
;             __builtin_amdgcn_sched_barrier(0);
; #pragma unroll
;             for (int tt = 0; tt < 16; ++tt) { const int j = 16 * tq + tt - 2 * (kb + i); if (j >= 0) acc[tt] = __builtin_amdgcn_mfma_f32_16x16x32_bf16(af[tt], cur[i], acc[tt], 0, 0, 0); }
;             __builtin_amdgcn_sched_barrier(0); }
; #pragma unroll
;         for (int i = 0; i < 8; ++i) cur[i] = nxt[i];
;     }
	v_mfma_f32_16x16x32_bf16 v[34:37], v[138:141], v[4:7], v[34:37]
	v_mfma_f32_16x16x32_bf16 v[38:41], v[134:137], v[4:7], v[38:41]
	ds_read_b128 v[134:137], v2 offset:0
	ds_read_b128 v[138:141], v2 offset:1024
	v_mfma_f32_16x16x32_bf16 v[42:45], v[194:197], v[4:7], v[42:45]
	v_mfma_f32_16x16x32_bf16 v[46:49], v[190:193], v[4:7], v[46:49]
	v_mfma_f32_16x16x32_bf16 v[50:53], v[186:189], v[4:7], v[50:53]
	v_mfma_f32_16x16x32_bf16 v[54:57], v[182:185], v[4:7], v[54:57]
	v_mfma_f32_16x16x32_bf16 v[58:61], v[178:181], v[4:7], v[58:61]
	v_mfma_f32_16x16x32_bf16 v[62:65], v[174:177], v[4:7], v[62:65]
	v_mfma_f32_16x16x32_bf16 v[66:69], v[170:173], v[4:7], v[66:69]
	v_mfma_f32_16x16x32_bf16 v[70:73], v[166:169], v[4:7], v[70:73]
	v_mfma_f32_16x16x32_bf16 v[74:77], v[162:165], v[4:7], v[74:77]
	v_mfma_f32_16x16x32_bf16 v[78:81], v[158:161], v[4:7], v[78:81]
	v_mfma_f32_16x16x32_bf16 v[82:85], v[154:157], v[4:7], v[82:85]
	v_mfma_f32_16x16x32_bf16 v[86:89], v[150:153], v[4:7], v[86:89]
	s_waitcnt lgkmcnt(2)
	v_mfma_f32_16x16x32_bf16 v[90:93], v[146:149], v[4:7], v[90:93]
	v_mfma_f32_16x16x32_bf16 v[94:97], v[142:145], v[4:7], v[94:97]
	v_lshl_add_u64 v[102:103], s[40:41], 0, v[200:201]
	s_add_u32 s40, s40, 0x1400
	s_addc_u32 s41, s41, 0
	global_load_dwordx4 v[4:7], v[102:103], off offset:1280
	v_add_u32_e32 v2, 0xffffc000, v2
	s_add_i32 s42, s42, -1
	s_cmp_lg_u32 s42, 0
	s_cbranch_scc1 .Ls5y_full
.Ls5y_tail:
	s_waitcnt lgkmcnt(0)
	s_waitcnt vmcnt(7)
	v_mfma_f32_16x16x32_bf16 v[34:37], v[194:197], v[98:101], v[34:37]
	v_mfma_f32_16x16x32_bf16 v[38:41], v[190:193], v[98:101], v[38:41]
	v_mfma_f32_16x16x32_bf16 v[42:45], v[186:189], v[98:101], v[42:45]
	v_mfma_f32_16x16x32_bf16 v[46:49], v[182:185], v[98:101], v[46:49]
	v_mfma_f32_16x16x32_bf16 v[50:53], v[178:181], v[98:101], v[50:53]
	v_mfma_f32_16x16x32_bf16 v[54:57], v[174:177], v[98:101], v[54:57]
	v_mfma_f32_16x16x32_bf16 v[58:61], v[170:173], v[98:101], v[58:61]
	v_mfma_f32_16x16x32_bf16 v[62:65], v[166:169], v[98:101], v[62:65]
	v_mfma_f32_16x16x32_bf16 v[66:69], v[162:165], v[98:101], v[66:69]
	v_mfma_f32_16x16x32_bf16 v[70:73], v[158:161], v[98:101], v[70:73]
	v_mfma_f32_16x16x32_bf16 v[74:77], v[154:157], v[98:101], v[74:77]
	v_mfma_f32_16x16x32_bf16 v[78:81], v[150:153], v[98:101], v[78:81]
	v_mfma_f32_16x16x32_bf16 v[82:85], v[146:149], v[98:101], v[82:85]
	v_mfma_f32_16x16x32_bf16 v[86:89], v[142:145], v[98:101], v[86:89]
	v_mfma_f32_16x16x32_bf16 v[90:93], v[138:141], v[98:101], v[90:93]
	v_mfma_f32_16x16x32_bf16 v[94:97], v[134:137], v[98:101], v[94:97]
	s_waitcnt vmcnt(6)
	v_mfma_f32_16x16x32_bf16 v[34:37], v[186:189], v[30:33], v[34:37]
	v_mfma_f32_16x16x32_bf16 v[38:41], v[182:185], v[30:33], v[38:41]
	v_mfma_f32_16x16x32_bf16 v[42:45], v[178:181], v[30:33], v[42:45]
	v_mfma_f32_16x16x32_bf16 v[46:49], v[174:177], v[30:33], v[46:49]
	v_mfma_f32_16x16x32_bf16 v[50:53], v[170:173], v[30:33], v[50:53]
	v_mfma_f32_16x16x32_bf16 v[54:57], v[166:169], v[30:33], v[54:57]
	v_mfma_f32_16x16x32_bf16 v[58:61], v[162:165], v[30:33], v[58:61]
	v_mfma_f32_16x16x32_bf16 v[62:65], v[158:161], v[30:33], v[62:65]
	v_mfma_f32_16x16x32_bf16 v[66:69], v[154:157], v[30:33], v[66:69]
	v_mfma_f32_16x16x32_bf16 v[70:73], v[150:153], v[30:33], v[70:73]
	v_mfma_f32_16x16x32_bf16 v[74:77], v[146:149], v[30:33], v[74:77]
	v_mfma_f32_16x16x32_bf16 v[78:81], v[142:145], v[30:33], v[78:81]
	v_mfma_f32_16x16x32_bf16 v[82:85], v[138:141], v[30:33], v[82:85]
	v_mfma_f32_16x16x32_bf16 v[86:89], v[134:137], v[30:33], v[86:89]
	s_waitcnt vmcnt(5)
	v_mfma_f32_16x16x32_bf16 v[34:37], v[178:181], v[26:29], v[34:37]
	v_mfma_f32_16x16x32_bf16 v[38:41], v[174:177], v[26:29], v[38:41]
	v_mfma_f32_16x16x32_bf16 v[42:45], v[170:173], v[26:29], v[42:45]
	v_mfma_f32_16x16x32_bf16 v[46:49], v[166:169], v[26:29], v[46:49]
	v_mfma_f32_16x16x32_bf16 v[50:53], v[162:165], v[26:29], v[50:53]
	v_mfma_f32_16x16x32_bf16 v[54:57], v[158:161], v[26:29], v[54:57]
	v_mfma_f32_16x16x32_bf16 v[58:61], v[154:157], v[26:29], v[58:61]
	v_mfma_f32_16x16x32_bf16 v[62:65], v[150:153], v[26:29], v[62:65]
	v_mfma_f32_16x16x32_bf16 v[66:69], v[146:149], v[26:29], v[66:69]
	v_mfma_f32_16x16x32_bf16 v[70:73], v[142:145], v[26:29], v[70:73]
	v_mfma_f32_16x16x32_bf16 v[74:77], v[138:141], v[26:29], v[74:77]
	v_mfma_f32_16x16x32_bf16 v[78:81], v[134:137], v[26:29], v[78:81]
	s_waitcnt vmcnt(4)
	v_mfma_f32_16x16x32_bf16 v[34:37], v[170:173], v[22:25], v[34:37]
	v_mfma_f32_16x16x32_bf16 v[38:41], v[166:169], v[22:25], v[38:41]
	v_mfma_f32_16x16x32_bf16 v[42:45], v[162:165], v[22:25], v[42:45]
	v_mfma_f32_16x16x32_bf16 v[46:49], v[158:161], v[22:25], v[46:49]
	v_mfma_f32_16x16x32_bf16 v[50:53], v[154:157], v[22:25], v[50:53]
	v_mfma_f32_16x16x32_bf16 v[54:57], v[150:153], v[22:25], v[54:57]
	v_mfma_f32_16x16x32_bf16 v[58:61], v[146:149], v[22:25], v[58:61]
	v_mfma_f32_16x16x32_bf16 v[62:65], v[142:145], v[22:25], v[62:65]
	v_mfma_f32_16x16x32_bf16 v[66:69], v[138:141], v[22:25], v[66:69]
	v_mfma_f32_16x16x32_bf16 v[70:73], v[134:137], v[22:25], v[70:73]
	s_waitcnt vmcnt(3)
	v_mfma_f32_16x16x32_bf16 v[34:37], v[162:165], v[18:21], v[34:37]
	v_mfma_f32_16x16x32_bf16 v[38:41], v[158:161], v[18:21], v[38:41]
	v_mfma_f32_16x16x32_bf16 v[42:45], v[154:157], v[18:21], v[42:45]
	v_mfma_f32_16x16x32_bf16 v[46:49], v[150:153], v[18:21], v[46:49]
	v_mfma_f32_16x16x32_bf16 v[50:53], v[146:149], v[18:21], v[50:53]
	v_mfma_f32_16x16x32_bf16 v[54:57], v[142:145], v[18:21], v[54:57]
	v_mfma_f32_16x16x32_bf16 v[58:61], v[138:141], v[18:21], v[58:61]
	v_mfma_f32_16x16x32_bf16 v[62:65], v[134:137], v[18:21], v[62:65]
	s_waitcnt vmcnt(2)
	v_mfma_f32_16x16x32_bf16 v[34:37], v[154:157], v[12:15], v[34:37]
	v_mfma_f32_16x16x32_bf16 v[38:41], v[150:153], v[12:15], v[38:41]
	v_mfma_f32_16x16x32_bf16 v[42:45], v[146:149], v[12:15], v[42:45]
	v_mfma_f32_16x16x32_bf16 v[46:49], v[142:145], v[12:15], v[46:49]
	v_mfma_f32_16x16x32_bf16 v[50:53], v[138:141], v[12:15], v[50:53]
	v_mfma_f32_16x16x32_bf16 v[54:57], v[134:137], v[12:15], v[54:57]
	s_waitcnt vmcnt(1)
	v_mfma_f32_16x16x32_bf16 v[34:37], v[146:149], v[8:11], v[34:37]
	v_mfma_f32_16x16x32_bf16 v[38:41], v[142:145], v[8:11], v[38:41]
	v_mfma_f32_16x16x32_bf16 v[42:45], v[138:141], v[8:11], v[42:45]
	v_mfma_f32_16x16x32_bf16 v[46:49], v[134:137], v[8:11], v[46:49]
	s_waitcnt vmcnt(0)
	v_mfma_f32_16x16x32_bf16 v[34:37], v[138:141], v[4:7], v[34:37]
	v_mfma_f32_16x16x32_bf16 v[38:41], v[134:137], v[4:7], v[38:41]
